# attention: bias-table loads issued before the K loads and K waits made progressive (each 2-key-row round waits only for its own 8 loads instead of all 32 before the first QK MFMA)
# baseline (speedup 1.0000x reference)
; __device__ __forceinline__ void attn_phase(LAS unsigned char* lds, const bf16_t* QKV, const float* TBL  , bf16_t* O, int tid, int wave, int lane, int G) {
;     ...
;     for (int it = (int)blockIdx.x * NWAV + wave; it < 65536; it += G * NWAV) {
;         const int qt = it & 3, h = (it >> 2) & 15, r = (it >> 6) & 127, b = it >> 13;
;         const int r0 = min(max(r - 4, 0), 120), kc0 = qt == 0 ? 0 : (qt == 1 ? 8 : (qt == 2 ? 24 : 32));
;         const int c = 16 * qt + fr;
;         const size_t tokq = (size_t)b * SEQL + r * 64 + c;
;         const float* tb = TBL + ((size_t)(((r - r0) * 16 + h) * 4 + qt) * 16) * 256 + lane * 4;
;         bf16x8 qf[2];
;         const bf16_t* qh = QKV + ((size_t)(b * 16 + h) * SEQL) * 64; const bf16_t* kh = qh + (size_t)MTOK * DM; const bf16_t* vh = kh + (size_t)MTOK * DM;
;         {
;             const bf16_t* qsrc = qh + (size_t)(r * 64 + 16 * qt + (lane >> 3)) * 64 + (lane & 7) * 8;
;             const u32x4 q0 = *(const u32x4*)qsrc, q1 = *(const u32x4*)(qsrc + (size_t)8 * 64);
;             *(LAS u32x4*)(vt + (lane >> 3) * 144 + (lane & 7) * 16) = q0; *(LAS u32x4*)(vt + ((lane >> 3) + 8) * 144 + (lane & 7) * 16) = q1;
;             qf[0] = *(const LAS bf16x8*)(vt + fr * 144 + 16 * fq); qf[1] = *(const LAS bf16x8*)(vt + fr * 144 + 64 + 16 * fq);
;             asm volatile("s_waitcnt lgkmcnt(0)" ::: "memory"); }
;         const int vkey = lane >> 3, vch = lane & 7;
;         const bf16_t* vsrc = vh + (size_t)(r0 * 64 + kc0 + vkey) * 64 + vch * 8;
;         u32x4 vr[4][2][4];
;         f32x4 s[8][2]; u32x4 kr[4][2][4];
;         const bf16_t* ksrc = kh + (size_t)(r0 * 64 + kc0 + vkey) * 64 + vch * 8;
; #pragma unroll
;         for (int i = 0; i < 8; ++i) { const bf16_t* src = ksrc + (size_t)i * 64 * 64;
; #pragma unroll
;             for (int j = 0; j < 4; ++j) kr[i >> 1][i & 1][j] = *(const u32x4*)(src + (size_t)j * 8 * 64); }
; #pragma unroll
;         for (int i = 0; i < 8; ++i)
; #pragma unroll
;             for (int t = 0; t < 2; ++t) s[i][t] = i < 4 ? *(const f32x4*)(tb + (i * 2 + t) * 256) : (f32x4){0.f, 0.f, 0.f, 0.f};
;         __builtin_amdgcn_sched_barrier(0);
;         f32x4 tb2[4][2];
; #pragma unroll
;         for (int ip = 0; ip < 4; ++ip) {
; #pragma unroll
;             for (int rr = 0; rr < 2; ++rr) { LAS unsigned char* dst = vt + rr * 4608 + vkey * 144 + vch * 16;
; #pragma unroll
.LBB0_366:
	s_bfe_u32 s10, s12, 0x70006
	v_sub_u32_e64 v0, s10, 4 clamp
	s_bfe_u32 s17, s12, 0x40002
	v_readfirstlane_b32 s9, v0
	s_min_u32 s20, s9, 0x78
	s_lshl_b32 s18, s10, 6
	s_sub_i32 s10, s10, s20
	s_mov_b32 s101, s10
	s_ashr_i32 s8, s12, 13
	s_lshl_b32 s10, s10, 6
	s_lshl_b32 s11, s17, 2
	s_or_b32 s10, s10, s11
	s_lshl_b32 s21, s8, 4
	s_or_b32 s10, s10, s15
	s_or_b32 s30, s21, s17
	s_ashr_i32 s11, s10, 31
	s_ashr_i32 s31, s30, 31
	s_ashr_i32 s9, s8, 31
	s_lshl_b64 s[10:11], s[10:11], 14
	s_lshl_b64 s[30:31], s[30:31], 20
	s_add_u32 s30, s13, s30
	v_or_b32_e32 v0, s18, v164
	s_addc_u32 s31, s14, s31
	v_lshlrev_b32_e32 v0, 7, v0
	v_lshl_add_u64 v[2:3], s[30:31], 0, v[0:1]
	v_mov_b32_e32 v167, v1
	v_lshl_add_u64 v[6:7], v[2:3], 0, v[166:167]
	global_load_dwordx4 v[2:5], v[6:7], off
	s_nop 0
	global_load_dwordx4 v[6:9], v[6:7], off offset:1024
	s_lshl_b32 s20, s20, 6
	s_or_b32 s19, s19, s20
	v_or_b32_e32 v0, s19, v165
	v_lshlrev_b32_e32 v0, 7, v0
	v_lshl_add_u64 v[10:11], s[30:31], 0, v[0:1]
	v_lshl_add_u64 v[18:19], v[10:11], 0, v[166:167]
	s_brev_b32 s19, 16
	v_add_co_u32_e32 v20, vcc, s19, v18
	s_mov_b32 s19, 0x8002000
	s_nop 0
	v_addc_co_u32_e32 v21, vcc, 0, v19, vcc
	v_add_co_u32_e32 v40, vcc, s19, v18
	s_mov_b32 s19, 0x8004000
	s_nop 0
	v_addc_co_u32_e32 v41, vcc, 0, v19, vcc
	v_add_co_u32_e32 v56, vcc, s19, v18
	s_mov_b32 s19, 0x8006000
	s_nop 0
	v_addc_co_u32_e32 v57, vcc, 0, v19, vcc
	v_add_co_u32_e32 v72, vcc, s19, v18
	s_mov_b32 s19, 0x8008000
	s_nop 0
	v_addc_co_u32_e32 v73, vcc, 0, v19, vcc
	v_add_co_u32_e32 v88, vcc, s19, v18
	s_mov_b32 s19, 0x800a000
	s_nop 0
	v_addc_co_u32_e32 v89, vcc, 0, v19, vcc
	v_add_co_u32_e32 v104, vcc, s19, v18
	s_mov_b32 s19, 0x800c000
	s_nop 0
	v_addc_co_u32_e32 v105, vcc, 0, v19, vcc
	v_add_u32_e32 v0, v200, v201
	s_mov_b64 s[30:31], 0x8000000
	v_add_co_u32_e32 v120, vcc, s19, v18
	v_lshl_add_u64 v[24:25], v[18:19], 0, s[30:31]
	s_nop 0
	v_addc_co_u32_e32 v121, vcc, 0, v19, vcc
	s_mov_b32 s19, 0x800e000
	v_add_co_u32_e32 v128, vcc, s19, v18
	v_lshl_add_u64 v[192:193], v[162:163], 0, s[10:11]
	s_nop 0
	v_addc_co_u32_e32 v129, vcc, 0, v19, vcc
	s_movk_i32 s10, 0x1000
	v_add_co_u32_e32 v140, vcc, s10, v192
	s_movk_i32 s10, 0x2000
	s_nop 0
	v_addc_co_u32_e32 v141, vcc, 0, v193, vcc
	v_add_co_u32_e32 v194, vcc, s10, v192
	s_lshl_b64 s[8:9], s[8:9], 13
	s_nop 0
	v_addc_co_u32_e32 v195, vcc, 0, v193, vcc
	s_or_b32 s8, s8, s18
	s_cmp_eq_u32 s101, s100
	s_cbranch_scc1 .Lattn_tb_res
	global_load_dwordx4 v[222:225], v[192:193], off
	global_load_dwordx4 v[226:229], v[192:193], off offset:1024
	global_load_dwordx4 v[230:233], v[192:193], off offset:2048
	global_load_dwordx4 v[238:241], v[192:193], off offset:3072
	global_load_dwordx4 v[242:245], v[140:141], off offset:1024
	global_load_dwordx4 v[246:249], v[140:141], off offset:2048
	s_mov_b32 s100, s101
.Lattn_tb_res:
	global_load_dwordx4 v[184:187], v[194:195], off offset:-4096
	global_load_dwordx4 v[188:191], v[140:141], off offset:3072
	global_load_dwordx4 v[10:13], v[24:25], off offset:1024
	global_load_dwordx4 v[14:17], v[24:25], off offset:2048
	s_nop 0
	global_load_dwordx4 v[20:23], v[20:21], off
	s_nop 0
	global_load_dwordx4 v[24:27], v[24:25], off offset:3072
	s_nop 0
	global_load_dwordx4 v[28:31], v[40:41], off
	global_load_dwordx4 v[32:35], v[40:41], off offset:1024
	global_load_dwordx4 v[36:39], v[40:41], off offset:2048
	s_nop 0
	global_load_dwordx4 v[40:43], v[40:41], off offset:3072
	s_nop 0
	global_load_dwordx4 v[44:47], v[56:57], off
	global_load_dwordx4 v[48:51], v[56:57], off offset:1024
	global_load_dwordx4 v[52:55], v[56:57], off offset:2048
	s_nop 0
	global_load_dwordx4 v[56:59], v[56:57], off offset:3072
	s_nop 0
	global_load_dwordx4 v[60:63], v[72:73], off
	global_load_dwordx4 v[64:67], v[72:73], off offset:1024
	global_load_dwordx4 v[68:71], v[72:73], off offset:2048
	s_nop 0
	global_load_dwordx4 v[72:75], v[72:73], off offset:3072
	s_nop 0
	global_load_dwordx4 v[76:79], v[88:89], off
	global_load_dwordx4 v[80:83], v[88:89], off offset:1024
	global_load_dwordx4 v[84:87], v[88:89], off offset:2048
	s_nop 0
	global_load_dwordx4 v[88:91], v[88:89], off offset:3072
	s_nop 0
	global_load_dwordx4 v[92:95], v[104:105], off
	global_load_dwordx4 v[96:99], v[104:105], off offset:1024
	global_load_dwordx4 v[100:103], v[104:105], off offset:2048
	s_nop 0
	global_load_dwordx4 v[104:107], v[104:105], off offset:3072
	s_nop 0
	global_load_dwordx4 v[108:111], v[120:121], off
	global_load_dwordx4 v[112:115], v[120:121], off offset:1024
	global_load_dwordx4 v[116:119], v[120:121], off offset:2048
	s_nop 0
	global_load_dwordx4 v[120:123], v[120:121], off offset:3072
	s_nop 0
	global_load_dwordx4 v[124:127], v[128:129], off
	global_load_dwordx4 v[158:161], v[128:129], off offset:1024
	global_load_dwordx4 v[168:171], v[128:129], off offset:2048
	global_load_dwordx4 v[172:175], v[128:129], off offset:3072
	s_nop 0
	s_waitcnt vmcnt(34)
	ds_write_b128 v209, v[2:5]
	ds_write_b128 v209, v[6:9] offset:1152
	ds_read_b128 v[6:9], v0
	ds_read_b128 v[2:5], v0 offset:64
	s_waitcnt lgkmcnt(0)
	s_waitcnt vmcnt(29)
	ds_write_b128 v209, v[20:23]
	ds_write_b128 v209, v[10:13] offset:1152
	ds_write_b128 v209, v[14:17] offset:2304
	s_waitcnt vmcnt(28)
	ds_write_b128 v209, v[24:27] offset:3456
	s_waitcnt vmcnt(27)
	ds_write_b128 v209, v[28:31] offset:4608
	s_waitcnt vmcnt(26)
	ds_write_b128 v209, v[32:35] offset:5760
	s_waitcnt vmcnt(25)
	ds_write_b128 v209, v[36:39] offset:6912
	s_waitcnt vmcnt(24)
	ds_write_b128 v209, v[40:43] offset:8064
	ds_read_b128 v[10:13], v210
	ds_read_b128 v[14:17], v210 offset:64
	ds_read_b128 v[20:23], v210 offset:2304
	ds_read_b128 v[24:27], v210 offset:2368
	s_movk_i32 s10, 0x3000
	s_waitcnt lgkmcnt(3)
; __device__ __forceinline__ void attn_phase(LAS unsigned char* lds, const bf16_t* QKV, const float* TBL  , bf16_t* O, int tid, int wave, int lane, int G) {
;     ...
;         for (int ip = 0; ip < 4; ++ip) {
; #pragma unroll
;             for (int rr = 0; rr < 2; ++rr) { LAS unsigned char* dst = vt + rr * 4608 + vkey * 144 + vch * 16;
; #pragma unroll
;                 for (int j = 0; j < 4; ++j) *(LAS u32x4*)(dst + j * 8 * 144) = kr[ip][rr][j]; }
;             if (ip == 1) {
; #pragma unroll
;                 for (int i = 0; i < 4; ++i)
; #pragma unroll
;                     for (int t = 0; t < 2; ++t) tb2[i][t] = *(const f32x4*)(tb + ((i + 4) * 2 + t) * 256); }
; #pragma unroll
;             for (int rr = 0; rr < 2; ++rr)
; #pragma unroll
;                 for (int t = 0; t < 2; ++t) { const LAS unsigned char* kp = vt + rr * 4608 + (16 * t + fr) * 144 + 16 * fq;
;                     const bf16x8 k0 = *(const LAS bf16x8*)kp, k1 = *(const LAS bf16x8*)(kp + 64);
;                     s[2 * ip + rr][t] = __builtin_amdgcn_mfma_f32_16x16x32_bf16(k0, qf[0], s[2 * ip + rr][t], 0, 0, 0); s[2 * ip + rr][t] = __builtin_amdgcn_mfma_f32_16x16x32_bf16(k1, qf[1], s[2 * ip + rr][t], 0, 0, 0); }
;             asm volatile("s_waitcnt lgkmcnt(0)" ::: "memory");
;         }
; #pragma unroll
;         for (int i = 0; i < 4; ++i)
; #pragma unroll
;             for (int t = 0; t < 2; ++t) s[i + 4][t] = s[i + 4][t] + tb2[i][t];
	v_mfma_f32_16x16x32_bf16 v[10:13], v[10:13], v[6:9], v[222:225]
	s_waitcnt lgkmcnt(2)
	v_mfma_f32_16x16x32_bf16 v[154:157], v[14:17], v[2:5], v[10:13]
	ds_read_b128 v[14:17], v210 offset:4672
	s_nop 4
	ds_read_b128 v[10:13], v210 offset:4608
	s_waitcnt lgkmcnt(3)
	v_mfma_f32_16x16x32_bf16 v[20:23], v[20:23], v[6:9], v[226:229]
	s_waitcnt lgkmcnt(2)
	v_mfma_f32_16x16x32_bf16 v[150:153], v[24:27], v[2:5], v[20:23]
	s_nop 5
	ds_read_b128 v[20:23], v210 offset:6912
	ds_read_b128 v[24:27], v210 offset:6976
	s_waitcnt lgkmcnt(0)
	s_waitcnt vmcnt(16)
	ds_write_b128 v209, v[44:47]
	ds_write_b128 v209, v[48:51] offset:1152
	ds_write_b128 v209, v[52:55] offset:2304
	s_waitcnt lgkmcnt(5)
	v_mfma_f32_16x16x32_bf16 v[10:13], v[10:13], v[6:9], v[230:233]
	ds_write_b128 v209, v[56:59] offset:3456
	ds_write_b128 v209, v[60:63] offset:4608
	ds_write_b128 v209, v[64:67] offset:5760
	ds_write_b128 v209, v[68:71] offset:6912
	ds_write_b128 v209, v[72:75] offset:8064
	v_add_co_u32_e32 v48, vcc, s10, v192
	v_mfma_f32_16x16x32_bf16 v[142:145], v[14:17], v[2:5], v[10:13]
	ds_read_b128 v[14:17], v210
	v_addc_co_u32_e32 v49, vcc, 0, v193, vcc
	s_waitcnt lgkmcnt(10)
	v_mfma_f32_16x16x32_bf16 v[10:13], v[20:23], v[6:9], v[238:241]
	s_mov_b64 s[10:11], 0x10000000
	s_waitcnt lgkmcnt(9)
	v_mfma_f32_16x16x32_bf16 v[146:149], v[24:27], v[2:5], v[10:13]
	s_nop 4
	ds_read_b128 v[10:13], v210 offset:64
	s_waitcnt lgkmcnt(1)
	v_mfma_f32_16x16x32_bf16 v[14:17], v[14:17], v[6:9], v[184:187]
	ds_read_b128 v[20:23], v210 offset:2304
	ds_read_b128 v[24:27], v210 offset:2368
	s_waitcnt lgkmcnt(2)
	v_mfma_f32_16x16x32_bf16 v[138:141], v[10:13], v[2:5], v[14:17]
	global_load_dwordx4 v[10:13], v[194:195], off
	s_nop 2
	global_load_dwordx4 v[14:17], v[194:195], off offset:1024
	ds_read_b128 v[28:31], v210 offset:4608
	global_load_dwordx4 v[32:35], v[194:195], off offset:2048
	global_load_dwordx4 v[36:39], v[194:195], off offset:3072
	s_waitcnt lgkmcnt(2)
	v_mfma_f32_16x16x32_bf16 v[20:23], v[20:23], v[6:9], v[242:245]
	ds_read_b128 v[40:43], v210 offset:4672
	s_waitcnt lgkmcnt(2)
	v_mfma_f32_16x16x32_bf16 v[134:137], v[24:27], v[2:5], v[20:23]
	s_waitcnt lgkmcnt(1)
	v_mfma_f32_16x16x32_bf16 v[20:23], v[28:31], v[6:9], v[246:249]
	global_load_dwordx4 v[24:27], v[48:49], off
	global_load_dwordx4 v[28:31], v[48:49], off offset:1024
	global_load_dwordx4 v[44:47], v[48:49], off offset:2048
	s_nop 0
	global_load_dwordx4 v[48:51], v[48:49], off offset:3072
	s_waitcnt lgkmcnt(0)
	v_mfma_f32_16x16x32_bf16 v[130:133], v[40:43], v[2:5], v[20:23]
	s_nop 2
	ds_read_b128 v[20:23], v210 offset:6912
	ds_read_b128 v[40:43], v210 offset:6976
	s_waitcnt lgkmcnt(0)
	s_waitcnt vmcnt(16)
	ds_write_b128 v209, v[76:79]
	ds_write_b128 v209, v[80:83] offset:1152
	ds_write_b128 v209, v[84:87] offset:2304
	ds_write_b128 v209, v[88:91] offset:3456
	ds_write_b128 v209, v[92:95] offset:4608
	ds_write_b128 v209, v[96:99] offset:5760
	ds_write_b128 v209, v[100:103] offset:6912
	ds_write_b128 v209, v[104:107] offset:8064
	ds_read_b128 v[52:55], v210
	ds_read_b128 v[56:59], v210 offset:64
	s_waitcnt lgkmcnt(1)
	v_mfma_f32_16x16x32_bf16 v[52:55], v[52:55], v[6:9], 0
	ds_read_b128 v[60:63], v210 offset:2304
	ds_read_b128 v[64:67], v210 offset:4608
	s_waitcnt lgkmcnt(2)
	v_mfma_f32_16x16x32_bf16 v[52:55], v[56:59], v[2:5], v[52:55]
	ds_read_b128 v[56:59], v210 offset:2368
	s_waitcnt lgkmcnt(2)
	v_mfma_f32_16x16x32_bf16 v[60:63], v[60:63], v[6:9], 0
	s_waitcnt vmcnt(7)
	s_nop 3
	v_pk_add_f32 v[196:197], v[12:13], v[54:55]
	s_waitcnt lgkmcnt(0)
	v_mfma_f32_16x16x32_bf16 v[56:59], v[56:59], v[2:5], v[60:63]
	v_add_f32_e64 v198, v10, v52
	v_add_f32_e64 v199, v11, v53
	s_nop 0
	ds_read_b128 v[60:63], v210 offset:4672
	v_mfma_f32_16x16x32_bf16 v[64:67], v[64:67], v[6:9], 0
	ds_read_b128 v[68:71], v210 offset:6912
	ds_read_b128 v[72:75], v210 offset:6976
	s_waitcnt lgkmcnt(0)
	ds_write_b128 v209, v[108:111]
	ds_write_b128 v209, v[112:115] offset:1152
	ds_write_b128 v209, v[116:119] offset:2304
	ds_write_b128 v209, v[120:123] offset:3456
	ds_write_b128 v209, v[124:127] offset:4608
	ds_write_b128 v209, v[158:161] offset:5760
	ds_write_b128 v209, v[168:171] offset:6912
	ds_write_b128 v209, v[172:175] offset:8064
	s_waitcnt lgkmcnt(10)
	v_mfma_f32_16x16x32_bf16 v[60:63], v[60:63], v[2:5], v[64:67]
	ds_read_b128 v[76:79], v210 offset:2304
	s_waitcnt vmcnt(6)
	v_pk_add_f32 v[192:193], v[16:17], v[58:59]
	v_pk_add_f32 v[194:195], v[14:15], v[56:57]
	s_waitcnt lgkmcnt(10)
	v_mfma_f32_16x16x32_bf16 v[64:67], v[68:71], v[6:9], 0
	ds_read_b128 v[68:71], v210
	s_waitcnt lgkmcnt(10)
	v_mfma_f32_16x16x32_bf16 v[64:67], v[72:75], v[2:5], v[64:67]
	ds_read_b128 v[72:75], v210 offset:64
	s_waitcnt lgkmcnt(1)
	v_mfma_f32_16x16x32_bf16 v[68:71], v[68:71], v[6:9], 0
	s_waitcnt vmcnt(4)
	s_nop 3
	v_pk_add_f32 v[184:185], v[38:39], v[66:67]
	s_waitcnt lgkmcnt(0)
	v_mfma_f32_16x16x32_bf16 v[68:71], v[72:75], v[2:5], v[68:71]
	ds_read_b128 v[72:75], v210 offset:2368
	ds_read_b128 v[80:83], v210 offset:4608
	ds_read_b128 v[84:87], v210 offset:4672
	ds_read_b128 v[88:91], v210 offset:6912
	ds_read_b128 v[92:95], v210 offset:6976
	s_waitcnt lgkmcnt(0)
	v_mfma_f32_16x16x32_bf16 v[20:23], v[20:23], v[6:9], v[188:191]
	v_add_f32_e64 v186, v36, v64
	v_add_f32_e64 v187, v37, v65
	s_waitcnt vmcnt(3)
	v_pk_add_f32 v[180:181], v[26:27], v[70:71]
	v_pk_add_f32 v[182:183], v[24:25], v[68:69]
	v_mfma_f32_16x16x32_bf16 v[76:79], v[76:79], v[6:9], 0
	v_add_f32_e64 v188, v34, v62
	v_add_f32_e64 v189, v35, v63
	v_pk_add_f32 v[190:191], v[32:33], v[60:61]
	s_waitcnt lgkmcnt(3)
	v_mfma_f32_16x16x32_bf16 v[10:13], v[80:83], v[6:9], 0
	s_waitcnt lgkmcnt(1)
; __device__ __forceinline__ void attn_phase(LAS unsigned char* lds, const bf16_t* QKV, const float* TBL  , bf16_t* O, int tid, int wave, int lane, int G) {
;     ...
; #pragma unroll
;             for (int rr = 0; rr < 2; ++rr)
; #pragma unroll
;                 for (int t = 0; t < 2; ++t) { const LAS unsigned char* kp = vt + rr * 4608 + (16 * t + fr) * 144 + 16 * fq;
;                     const bf16x8 k0 = *(const LAS bf16x8*)kp, k1 = *(const LAS bf16x8*)(kp + 64);
;                     s[2 * ip + rr][t] = __builtin_amdgcn_mfma_f32_16x16x32_bf16(k0, qf[0], s[2 * ip + rr][t], 0, 0, 0); s[2 * ip + rr][t] = __builtin_amdgcn_mfma_f32_16x16x32_bf16(k1, qf[1], s[2 * ip + rr][t], 0, 0, 0); }
;             asm volatile("s_waitcnt lgkmcnt(0)" ::: "memory");
;         }
; #pragma unroll
;         for (int i = 0; i < 4; ++i)
; #pragma unroll
;             for (int t = 0; t < 2; ++t) s[i + 4][t] = s[i + 4][t] + tb2[i][t];
;         __builtin_amdgcn_sched_barrier(0);
; #pragma unroll
;         for (int i = 0; i < 8; ++i) { const bf16_t* src = vsrc + (size_t)i * 64 * 64;
; #pragma unroll
;             for (int j = 0; j < 4; ++j) vr[i >> 1][i & 1][j] = *(const u32x4*)(src + (size_t)j * 8 * 64); }
;         __builtin_amdgcn_sched_barrier(0);
;         float mx = -1e30f;
; #pragma unroll
;         for (int i = 0; i < 8; ++i)
; #pragma unroll
;             for (int t = 0; t < 2; ++t) mx = fmaxf(fmaxf(mx, fmaxf(s[i][t][0], s[i][t][1])), fmaxf(s[i][t][2], s[i][t][3]));
;         mx = fmaxf(mx, __shfl_xor(mx, 16)); mx = fmaxf(mx, __shfl_xor(mx, 32));
	v_mfma_f32_16x16x32_bf16 v[6:9], v[88:91], v[6:9], 0
	v_mfma_f32_16x16x32_bf16 v[72:75], v[72:75], v[2:5], v[76:79]
	v_mfma_f32_16x16x32_bf16 v[10:13], v[84:87], v[2:5], v[10:13]
	s_waitcnt lgkmcnt(0)
	v_mfma_f32_16x16x32_bf16 v[6:9], v[92:95], v[2:5], v[6:9]
	s_waitcnt vmcnt(2)
	s_nop 3
	v_pk_add_f32 v[176:177], v[30:31], v[74:75]
	v_pk_add_f32 v[178:179], v[28:29], v[72:73]
	s_waitcnt vmcnt(1)
	v_pk_add_f32 v[172:173], v[46:47], v[12:13]
	v_pk_add_f32 v[174:175], v[44:45], v[10:11]
	v_mfma_f32_16x16x32_bf16 v[158:161], v[40:43], v[2:5], v[20:23]
	s_waitcnt vmcnt(0)
	v_pk_add_f32 v[168:169], v[50:51], v[8:9]
	v_pk_add_f32 v[170:171], v[48:49], v[6:7]
	v_lshl_add_u64 v[2:3], v[18:19], 0, s[10:11]
	v_add_co_u32_e32 v4, vcc, s73, v18
	s_mov_b32 s10, 0x10002000
	s_nop 0
	v_addc_co_u32_e32 v5, vcc, 0, v19, vcc
	global_load_dwordx4 v[98:101], v[2:3], off offset:1024
	global_load_dwordx4 v[102:105], v[2:3], off offset:2048
	global_load_dwordx4 v[110:113], v[4:5], off
	global_load_dwordx4 v[106:109], v[2:3], off offset:3072
	v_add_co_u32_e32 v2, vcc, s10, v18
	s_mov_b32 s10, 0x10004000
	s_nop 0
	v_addc_co_u32_e32 v3, vcc, 0, v19, vcc
	global_load_dwordx4 v[114:117], v[2:3], off
	global_load_dwordx4 v[118:121], v[2:3], off offset:1024
	global_load_dwordx4 v[122:125], v[2:3], off offset:2048
	global_load_dwordx4 v[126:129], v[2:3], off offset:3072
	v_add_co_u32_e32 v2, vcc, s10, v18
	s_mov_b32 s10, 0x10006000
	s_nop 0
	v_addc_co_u32_e32 v3, vcc, 0, v19, vcc
	global_load_dwordx4 v[66:69], v[2:3], off
	global_load_dwordx4 v[70:73], v[2:3], off offset:1024
	global_load_dwordx4 v[74:77], v[2:3], off offset:2048
	global_load_dwordx4 v[78:81], v[2:3], off offset:3072
	v_add_co_u32_e32 v2, vcc, s10, v18
	s_mov_b32 s10, 0x10008000
	s_nop 0
	v_addc_co_u32_e32 v3, vcc, 0, v19, vcc
	global_load_dwordx4 v[82:85], v[2:3], off
	global_load_dwordx4 v[86:89], v[2:3], off offset:1024
	global_load_dwordx4 v[90:93], v[2:3], off offset:2048
	global_load_dwordx4 v[94:97], v[2:3], off offset:3072
	v_add_co_u32_e32 v2, vcc, s10, v18
	s_mov_b32 s10, 0x1000a000
	s_nop 0
	v_addc_co_u32_e32 v3, vcc, 0, v19, vcc
	global_load_dwordx4 v[34:37], v[2:3], off
	global_load_dwordx4 v[38:41], v[2:3], off offset:1024
	global_load_dwordx4 v[42:45], v[2:3], off offset:2048
	global_load_dwordx4 v[46:49], v[2:3], off offset:3072
	v_add_co_u32_e32 v2, vcc, s10, v18
	s_mov_b32 s10, 0x1000c000
	s_nop 0
	v_addc_co_u32_e32 v3, vcc, 0, v19, vcc
	v_add_co_u32_e32 v14, vcc, s10, v18
	s_mov_b32 s10, 0x1000e000
	s_nop 0
	v_addc_co_u32_e32 v15, vcc, 0, v19, vcc
	v_add_co_u32_e32 v30, vcc, s10, v18
	global_load_dwordx4 v[50:53], v[2:3], off
	global_load_dwordx4 v[54:57], v[2:3], off offset:1024
	global_load_dwordx4 v[58:61], v[2:3], off offset:2048
	global_load_dwordx4 v[62:65], v[2:3], off offset:3072
	v_addc_co_u32_e32 v31, vcc, 0, v19, vcc
	global_load_dwordx4 v[2:5], v[14:15], off
	global_load_dwordx4 v[6:9], v[14:15], off offset:1024
	global_load_dwordx4 v[10:13], v[14:15], off offset:2048
	s_nop 0
	global_load_dwordx4 v[14:17], v[14:15], off offset:3072
	s_nop 0
	global_load_dwordx4 v[18:21], v[30:31], off
	global_load_dwordx4 v[22:25], v[30:31], off offset:1024
	global_load_dwordx4 v[26:29], v[30:31], off offset:2048
	s_nop 0
	global_load_dwordx4 v[30:33], v[30:31], off offset:3072
	v_max_f32_e32 v0, v155, v155
	v_max_f32_e32 v204, v154, v154
	v_max_f32_e32 v0, v204, v0
	v_max_f32_e32 v204, v157, v157
	v_max_f32_e32 v205, v156, v156
	v_max_f32_e32 v204, v205, v204
	s_mov_b32 s10, 0xf149f2ca
	v_max3_f32 v0, v0, s10, v204
	v_max_f32_e32 v204, v151, v151
	v_max_f32_e32 v205, v150, v150
	v_max_f32_e32 v204, v205, v204
	v_max_f32_e32 v205, v153, v153
	v_max_f32_e32 v212, v152, v152
	v_max_f32_e32 v205, v212, v205
	v_max3_f32 v0, v0, v204, v205
	v_max_f32_e32 v204, v143, v143
	v_max_f32_e32 v205, v142, v142
	v_max_f32_e32 v204, v205, v204
	v_max_f32_e32 v205, v145, v145
	v_max_f32_e32 v212, v144, v144
	v_max_f32_e32 v205, v212, v205
	v_max3_f32 v0, v0, v204, v205
	v_max_f32_e32 v204, v147, v147
	v_max_f32_e32 v205, v146, v146
	v_max_f32_e32 v204, v205, v204
	v_max_f32_e32 v205, v149, v149
	v_max_f32_e32 v212, v148, v148
	v_max_f32_e32 v205, v212, v205
	v_max3_f32 v0, v0, v204, v205
	v_max_f32_e32 v204, v139, v139
	v_max_f32_e32 v205, v138, v138
	v_max_f32_e32 v204, v205, v204
	v_max_f32_e32 v205, v141, v141
	v_max_f32_e32 v212, v140, v140
	v_max_f32_e32 v205, v212, v205
	v_max3_f32 v0, v0, v204, v205
	v_max_f32_e32 v204, v135, v135
	v_max_f32_e32 v205, v134, v134
	v_max_f32_e32 v204, v205, v204
	v_max_f32_e32 v205, v137, v137
	v_max_f32_e32 v212, v136, v136
	v_max_f32_e32 v205, v212, v205
	v_max3_f32 v0, v0, v204, v205
	v_max_f32_e32 v204, v131, v131
	v_max_f32_e32 v205, v130, v130
	v_max_f32_e32 v204, v205, v204
	v_max_f32_e32 v205, v133, v133
	v_max_f32_e32 v212, v132, v132
	v_max_f32_e32 v205, v212, v205
	v_max3_f32 v0, v0, v204, v205
	v_max_f32_e32 v204, v159, v159
	v_max_f32_e32 v205, v158, v158
	v_max_f32_e32 v204, v205, v204
	v_max_f32_e32 v205, v161, v161
	v_max_f32_e32 v212, v160, v160
	v_max_f32_e32 v205, v212, v205
	v_max3_f32 v0, v0, v204, v205
	v_max_f32_e32 v204, v198, v199
	v_max_f32_e32 v205, v196, v197
	v_max3_f32 v0, v0, v204, v205
	v_max_f32_e32 v204, v194, v195
	v_max_f32_e32 v205, v192, v193
	v_max3_f32 v0, v0, v204, v205
	v_max_f32_e32 v204, v190, v191
	v_max_f32_e32 v205, v188, v189
	v_max3_f32 v0, v0, v204, v205
	v_max_f32_e32 v204, v186, v187
	v_max_f32_e32 v205, v184, v185
	v_max3_f32 v0, v0, v204, v205
	v_max_f32_e32 v204, v182, v183
	v_max_f32_e32 v205, v180, v181
	v_max3_f32 v0, v0, v204, v205
	v_max_f32_e32 v204, v178, v179
	v_max_f32_e32 v205, v176, v177
	v_max3_f32 v0, v0, v204, v205
	v_max_f32_e32 v204, v174, v175
	v_max_f32_e32 v205, v172, v173
	v_max3_f32 v0, v0, v204, v205
	v_max_f32_e32 v204, v170, v171
	v_max_f32_e32 v205, v168, v169
	v_max3_f32 v204, v0, v204, v205
	v_and_b32_e32 v205, 64, v237
	v_xor_b32_e32 v0, 16, v237
	v_add_u32_e32 v205, 64, v205
	v_cmp_lt_i32_e32 vcc, v0, v205
	s_waitcnt vmcnt(29)
; __device__ __forceinline__ u32x4 pack8(const f32x4 a, const f32x4 b) { u32x4 w; w.x = cvt_pk_bf16(a[0], a[1]); w.y = cvt_pk_bf16(a[2], a[3]); w.z = cvt_pk_bf16(b[0], b[1]); w.w = cvt_pk_bf16(b[2], b[3]); return w; }
; __device__ __forceinline__ void attn_phase(LAS unsigned char* lds, const bf16_t* QKV, const float* TBL  , bf16_t* O, int tid, int wave, int lane, int G) {
;     ...
;         mx = fmaxf(mx, __shfl_xor(mx, 16)); mx = fmaxf(mx, __shfl_xor(mx, 32));
;         float sum = 0.f;
; #pragma unroll
;         for (int i = 0; i < 8; ++i)
; #pragma unroll
;             for (int t = 0; t < 2; ++t)
; #pragma unroll
;                 for (int e = 0; e < 4; ++e) { const float pe = __builtin_amdgcn_exp2f(s[i][t][e] - mx); s[i][t][e] = pe; sum += pe; }
;         sum += __shfl_xor(sum, 16); sum += __shfl_xor(sum, 32);
;         f32x4 o[4];
; #pragma unroll
;         for (int dt = 0; dt < 4; ++dt) o[dt] = (f32x4){0.f, 0.f, 0.f, 0.f};
;         const unsigned ad = vt_addr + (unsigned)((4 * fq + (fr >> 2)) * 144 + 8 * (fr & 3));
; #pragma unroll
;         for (int ip = 0; ip < 4; ++ip) {
; #pragma unroll
;             for (int rr = 0; rr < 2; ++rr) { LAS unsigned char* dst = vt + rr * 4608 + vkey * 144 + vch * 16;
; #pragma unroll
;                 for (int j = 0; j < 4; ++j) *(LAS u32x4*)(dst + j * 8 * 144) = vr[ip][rr][j]; }
;             union { u32x4 w; bf16x8 v; } pf0, pf1; pf0.w = pack8(s[2 * ip][0], s[2 * ip][1]); pf1.w = pack8(s[2 * ip + 1][0], s[2 * ip + 1][1]);
;             s16x4 ta0, ta1, ta2, ta3, tb0, tb1, tb2, tb3, ua0, ua1, ua2, ua3, ub0, ub1, ub2, ub3;
;             asm volatile("ds_read_b64_tr_b16 %0, %16\n\tds_read_b64_tr_b16 %1, %16 offset:32\n\tds_read_b64_tr_b16 %2, %16 offset:64\n\tds_read_b64_tr_b16 %3, %16 offset:96\n\t"
;                          "ds_read_b64_tr_b16 %4, %16 offset:2304\n\tds_read_b64_tr_b16 %5, %16 offset:2336\n\tds_read_b64_tr_b16 %6, %16 offset:2368\n\tds_read_b64_tr_b16 %7, %16 offset:2400\n\t"
;                          "ds_read_b64_tr_b16 %8, %16 offset:4608\n\tds_read_b64_tr_b16 %9, %16 offset:4640\n\tds_read_b64_tr_b16 %10, %16 offset:4672\n\tds_read_b64_tr_b16 %11, %16 offset:4704\n\t"
;                          "ds_read_b64_tr_b16 %12, %16 offset:6912\n\tds_read_b64_tr_b16 %13, %16 offset:6944\n\tds_read_b64_tr_b16 %14, %16 offset:6976\n\tds_read_b64_tr_b16 %15, %16 offset:7008\n\ts_waitcnt lgkmcnt(0)"
	ds_write_b128 v209, v[110:113]
	ds_write_b128 v209, v[98:101] offset:1152
	ds_write_b128 v209, v[102:105] offset:2304
	s_waitcnt vmcnt(28)
	ds_write_b128 v209, v[106:109] offset:3456
	s_waitcnt vmcnt(27)
	ds_write_b128 v209, v[114:117] offset:4608
	s_waitcnt vmcnt(26)
	ds_write_b128 v209, v[118:121] offset:5760
	s_waitcnt vmcnt(25)
	ds_write_b128 v209, v[122:125] offset:6912
	s_waitcnt vmcnt(24)
	ds_write_b128 v209, v[126:129] offset:8064
	v_cndmask_b32_e32 v0, v237, v0, vcc
	v_lshlrev_b32_e32 v0, 2, v0
	ds_bpermute_b32 v212, v0, v204
	s_lshl_b32 s26, s17, 7
	s_add_i32 s12, s12, s38
	s_cmp_lt_i32 s12, 0x10000
	s_waitcnt lgkmcnt(0)
	v_max_f32_e32 v212, v212, v212
	v_max_f32_e32 v204, v204, v212
	v_xor_b32_e32 v212, 32, v237
	v_cmp_lt_i32_e32 vcc, v212, v205
	s_nop 1
	v_cndmask_b32_e32 v205, v237, v212, vcc
	v_lshlrev_b32_e32 v212, 2, v205
	ds_bpermute_b32 v205, v212, v204
	s_waitcnt lgkmcnt(0)
	v_max_f32_e32 v205, v205, v205
	v_max_f32_e32 v213, v204, v205
	v_sub_f32_e32 v154, v154, v213
	v_exp_f32_e32 v154, v154
	v_sub_f32_e32 v155, v155, v213
	v_exp_f32_e32 v155, v155
	v_sub_f32_e32 v156, v156, v213
	v_exp_f32_e32 v156, v156
	v_sub_f32_e32 v157, v157, v213
	v_exp_f32_e32 v157, v157
	v_sub_f32_e32 v150, v150, v213
	v_add_f32_e32 v204, 0, v154
	v_exp_f32_e32 v150, v150
	v_sub_f32_e32 v151, v151, v213
	v_add_f32_e32 v204, v155, v204
	v_exp_f32_e32 v151, v151
	v_sub_f32_e32 v152, v152, v213
	v_add_f32_e32 v204, v156, v204
	v_exp_f32_e32 v152, v152
	v_sub_f32_e32 v153, v153, v213
	v_add_f32_e32 v204, v157, v204
	v_exp_f32_e32 v153, v153
	v_sub_f32_e32 v142, v142, v213
	v_add_f32_e32 v204, v150, v204
	v_exp_f32_e32 v142, v142
	v_sub_f32_e32 v143, v143, v213
	v_add_f32_e32 v204, v151, v204
	v_exp_f32_e32 v143, v143
	v_sub_f32_e32 v144, v144, v213
	v_add_f32_e32 v204, v152, v204
	v_exp_f32_e32 v144, v144
	v_sub_f32_e32 v145, v145, v213
	v_add_f32_e32 v204, v153, v204
	v_exp_f32_e32 v145, v145
	v_sub_f32_e32 v146, v146, v213
	v_add_f32_e32 v204, v142, v204
	v_exp_f32_e32 v146, v146
	v_sub_f32_e32 v147, v147, v213
	v_add_f32_e32 v204, v143, v204
	v_exp_f32_e32 v147, v147
	v_sub_f32_e32 v148, v148, v213
	v_add_f32_e32 v204, v144, v204
	v_exp_f32_e32 v148, v148
	v_sub_f32_e32 v149, v149, v213
	v_add_f32_e32 v204, v145, v204
	v_exp_f32_e32 v149, v149
	v_sub_f32_e32 v138, v138, v213
	v_add_f32_e32 v204, v146, v204
	v_exp_f32_e32 v138, v138
	v_sub_f32_e32 v139, v139, v213
	v_add_f32_e32 v204, v147, v204
	v_exp_f32_e32 v139, v139
	v_sub_f32_e32 v140, v140, v213
	v_add_f32_e32 v204, v148, v204
	v_exp_f32_e32 v140, v140
	v_sub_f32_e32 v141, v141, v213
	v_add_f32_e32 v204, v149, v204
	v_exp_f32_e32 v141, v141
	v_sub_f32_e32 v134, v134, v213
	v_add_f32_e32 v204, v138, v204
	v_exp_f32_e32 v205, v134
	v_sub_f32_e32 v135, v135, v213
	v_add_f32_e32 v134, v139, v204
	v_exp_f32_e32 v204, v135
	v_sub_f32_e32 v135, v136, v213
	v_add_f32_e32 v134, v140, v134
	v_exp_f32_e32 v214, v135
	v_sub_f32_e32 v135, v137, v213
	v_add_f32_e32 v134, v141, v134
	v_exp_f32_e32 v215, v135
	v_sub_f32_e32 v130, v130, v213
	v_add_f32_e32 v134, v205, v134
	v_exp_f32_e32 v216, v130
	v_sub_f32_e32 v131, v131, v213
	v_add_f32_e32 v130, v204, v134
	v_exp_f32_e32 v217, v131
	v_sub_f32_e32 v131, v132, v213
	v_add_f32_e32 v130, v214, v130
	v_exp_f32_e32 v218, v131
	v_sub_f32_e32 v131, v133, v213
	v_add_f32_e32 v130, v215, v130
	v_exp_f32_e32 v219, v131
	v_sub_f32_e32 v131, v158, v213
	v_add_f32_e32 v130, v216, v130
	v_exp_f32_e32 v158, v131
	v_sub_f32_e32 v131, v159, v213
	v_add_f32_e32 v130, v217, v130
	v_exp_f32_e32 v159, v131
	v_sub_f32_e32 v131, v160, v213
	v_add_f32_e32 v130, v218, v130
	v_exp_f32_e32 v160, v131
	v_sub_f32_e32 v131, v161, v213
	v_add_f32_e32 v130, v219, v130
	v_exp_f32_e32 v161, v131
	v_sub_f32_e32 v131, v198, v213
	v_add_f32_e32 v130, v158, v130
	v_exp_f32_e32 v198, v131
	v_sub_f32_e32 v131, v199, v213
	v_add_f32_e32 v130, v159, v130
	v_exp_f32_e32 v199, v131
	v_sub_f32_e32 v131, v196, v213
	v_add_f32_e32 v130, v160, v130
	v_exp_f32_e32 v196, v131
	v_sub_f32_e32 v131, v197, v213
	v_add_f32_e32 v130, v161, v130
	v_exp_f32_e32 v197, v131
	v_sub_f32_e32 v131, v194, v213
	v_add_f32_e32 v130, v198, v130
	v_exp_f32_e32 v194, v131
	v_add_f32_e32 v130, v199, v130
	v_add_f32_e32 v130, v196, v130
	v_add_f32_e32 v130, v197, v130
	v_add_f32_e32 v220, v194, v130
	v_sub_f32_e32 v130, v195, v213
	v_exp_f32_e32 v195, v130
	v_sub_f32_e32 v130, v192, v213
	v_exp_f32_e32 v192, v130
	v_sub_f32_e32 v130, v193, v213
	v_exp_f32_e32 v193, v130
	v_cvt_pk_bf16_f32 v98, v154, v155
	v_cvt_pk_bf16_f32 v99, v156, v157
	v_cvt_pk_bf16_f32 v100, v150, v151
	v_cvt_pk_bf16_f32 v101, v152, v153
	v_cvt_pk_bf16_f32 v102, v142, v143
	v_cvt_pk_bf16_f32 v103, v144, v145
	v_cvt_pk_bf16_f32 v104, v146, v147
	v_cvt_pk_bf16_f32 v105, v148, v149
	ds_read_b64_tr_b16 v[134:135], v208
	ds_read_b64_tr_b16 v[130:131], v208 offset:32
	ds_read_b64_tr_b16 v[126:127], v208 offset:64
	ds_read_b64_tr_b16 v[122:123], v208 offset:96
	ds_read_b64_tr_b16 v[136:137], v208 offset:2304
	ds_read_b64_tr_b16 v[132:133], v208 offset:2336
	ds_read_b64_tr_b16 v[128:129], v208 offset:2368
	ds_read_b64_tr_b16 v[124:125], v208 offset:2400
	ds_read_b64_tr_b16 v[118:119], v208 offset:4608
	ds_read_b64_tr_b16 v[114:115], v208 offset:4640
	ds_read_b64_tr_b16 v[110:111], v208 offset:4672
	ds_read_b64_tr_b16 v[106:107], v208 offset:4704
	ds_read_b64_tr_b16 v[120:121], v208 offset:6912
	ds_read_b64_tr_b16 v[116:117], v208 offset:6944
	ds_read_b64_tr_b16 v[112:113], v208 offset:6976
	ds_read_b64_tr_b16 v[108:109], v208 offset:7008
	s_waitcnt lgkmcnt(0)
	v_sub_f32_e32 v143, v190, v213
	v_mfma_f32_16x16x32_bf16 v[134:137], v[134:137], v[98:101], 0
	s_waitcnt vmcnt(23)
; __device__ __forceinline__ void attn_phase(LAS unsigned char* lds, const bf16_t* QKV, const float* TBL  , bf16_t* O, int tid, int wave, int lane, int G) {
;     ...
;         for (int ip = 0; ip < 4; ++ip) {
; #pragma unroll
;             for (int rr = 0; rr < 2; ++rr) { LAS unsigned char* dst = vt + rr * 4608 + vkey * 144 + vch * 16;
; #pragma unroll
;                 for (int j = 0; j < 4; ++j) *(LAS u32x4*)(dst + j * 8 * 144) = vr[ip][rr][j]; }
;             union { u32x4 w; bf16x8 v; } pf0, pf1; pf0.w = pack8(s[2 * ip][0], s[2 * ip][1]); pf1.w = pack8(s[2 * ip + 1][0], s[2 * ip + 1][1]);
;             s16x4 ta0, ta1, ta2, ta3, tb0, tb1, tb2, tb3, ua0, ua1, ua2, ua3, ub0, ub1, ub2, ub3;
;             asm volatile("ds_read_b64_tr_b16 %0, %16\n\tds_read_b64_tr_b16 %1, %16 offset:32\n\tds_read_b64_tr_b16 %2, %16 offset:64\n\tds_read_b64_tr_b16 %3, %16 offset:96\n\t"
;                          "ds_read_b64_tr_b16 %4, %16 offset:2304\n\tds_read_b64_tr_b16 %5, %16 offset:2336\n\tds_read_b64_tr_b16 %6, %16 offset:2368\n\tds_read_b64_tr_b16 %7, %16 offset:2400\n\t"
;                          "ds_read_b64_tr_b16 %8, %16 offset:4608\n\tds_read_b64_tr_b16 %9, %16 offset:4640\n\tds_read_b64_tr_b16 %10, %16 offset:4672\n\tds_read_b64_tr_b16 %11, %16 offset:4704\n\t"
;                          "ds_read_b64_tr_b16 %12, %16 offset:6912\n\tds_read_b64_tr_b16 %13, %16 offset:6944\n\tds_read_b64_tr_b16 %14, %16 offset:6976\n\tds_read_b64_tr_b16 %15, %16 offset:7008\n\ts_waitcnt lgkmcnt(0)"
;                          : "=&v"(ta0), "=&v"(ta1), "=&v"(ta2), "=&v"(ta3), "=&v"(tb0), "=&v"(tb1), "=&v"(tb2), "=&v"(tb3), "=&v"(ua0), "=&v"(ua1), "=&v"(ua2), "=&v"(ua3), "=&v"(ub0), "=&v"(ub1), "=&v"(ub2), "=&v"(ub3) : "v"(ad) : "memory");
;             bf16x8 vf;
;             vf = (bf16x8){ta0[0], ta0[1], ta0[2], ta0[3], tb0[0], tb0[1], tb0[2], tb0[3]}; o[0] = __builtin_amdgcn_mfma_f32_16x16x32_bf16(vf, pf0.v, o[0], 0, 0, 0);
;             vf = (bf16x8){ta1[0], ta1[1], ta1[2], ta1[3], tb1[0], tb1[1], tb1[2], tb1[3]}; o[1] = __builtin_amdgcn_mfma_f32_16x16x32_bf16(vf, pf0.v, o[1], 0, 0, 0);
;             vf = (bf16x8){ta2[0], ta2[1], ta2[2], ta2[3], tb2[0], tb2[1], tb2[2], tb2[3]}; o[2] = __builtin_amdgcn_mfma_f32_16x16x32_bf16(vf, pf0.v, o[2], 0, 0, 0);
	ds_write_b128 v209, v[66:69]
	s_waitcnt vmcnt(22)
	ds_write_b128 v209, v[70:73] offset:1152
	s_waitcnt vmcnt(21)
	ds_write_b128 v209, v[74:77] offset:2304
	s_waitcnt vmcnt(20)
	ds_write_b128 v209, v[78:81] offset:3456
	s_waitcnt vmcnt(19)
	ds_write_b128 v209, v[82:85] offset:4608
	s_waitcnt vmcnt(18)
	ds_write_b128 v209, v[86:89] offset:5760
	s_waitcnt vmcnt(17)
	ds_write_b128 v209, v[90:93] offset:6912
	s_waitcnt vmcnt(16)
	ds_write_b128 v209, v[94:97] offset:8064
	v_cvt_pk_bf16_f32 v66, v138, v139
	v_cvt_pk_bf16_f32 v67, v140, v141
	v_mfma_f32_16x16x32_bf16 v[126:129], v[126:129], v[98:101], 0
	v_cvt_pk_bf16_f32 v68, v205, v204
	v_cvt_pk_bf16_f32 v69, v214, v215
	v_cvt_pk_bf16_f32 v70, v216, v217
	v_mfma_f32_16x16x32_bf16 v[130:133], v[130:133], v[98:101], 0
	v_cvt_pk_bf16_f32 v71, v218, v219
	v_cvt_pk_bf16_f32 v72, v158, v159
	v_cvt_pk_bf16_f32 v73, v160, v161
	v_mfma_f32_16x16x32_bf16 v[98:101], v[122:125], v[98:101], 0
	v_exp_f32_e32 v143, v143
	v_sub_f32_e32 v144, v191, v213
	v_add_f32_e32 v142, v195, v220
	v_mfma_f32_16x16x32_bf16 v[118:121], v[118:121], v[102:105], v[134:137]
	v_exp_f32_e32 v144, v144
	v_sub_f32_e32 v145, v188, v213
	v_add_f32_e32 v142, v192, v142
	v_mfma_f32_16x16x32_bf16 v[110:113], v[110:113], v[102:105], v[126:129]
	v_exp_f32_e32 v145, v145
	v_sub_f32_e32 v123, v189, v213
	v_add_f32_e32 v142, v193, v142
	v_mfma_f32_16x16x32_bf16 v[114:117], v[114:117], v[102:105], v[130:133]
	v_exp_f32_e32 v123, v123
	v_sub_f32_e32 v124, v186, v213
	v_add_f32_e32 v122, v143, v142
	v_mfma_f32_16x16x32_bf16 v[98:101], v[106:109], v[102:105], v[98:101]
	ds_read_b64_tr_b16 v[106:107], v208
	ds_read_b64_tr_b16 v[102:103], v208 offset:32
	ds_read_b64_tr_b16 v[94:95], v208 offset:64
	ds_read_b64_tr_b16 v[90:91], v208 offset:96
	ds_read_b64_tr_b16 v[108:109], v208 offset:2304
	ds_read_b64_tr_b16 v[104:105], v208 offset:2336
	ds_read_b64_tr_b16 v[96:97], v208 offset:2368
	ds_read_b64_tr_b16 v[92:93], v208 offset:2400
	ds_read_b64_tr_b16 v[86:87], v208 offset:4608
	ds_read_b64_tr_b16 v[82:83], v208 offset:4640
	ds_read_b64_tr_b16 v[78:79], v208 offset:4672
	ds_read_b64_tr_b16 v[74:75], v208 offset:4704
	ds_read_b64_tr_b16 v[88:89], v208 offset:6912
	ds_read_b64_tr_b16 v[84:85], v208 offset:6944
	ds_read_b64_tr_b16 v[80:81], v208 offset:6976
	ds_read_b64_tr_b16 v[76:77], v208 offset:7008
	s_waitcnt lgkmcnt(0)
	v_exp_f32_e32 v124, v124
	v_sub_f32_e32 v125, v187, v213
	v_mfma_f32_16x16x32_bf16 v[106:109], v[106:109], v[66:69], v[118:121]
	v_add_f32_e32 v122, v144, v122
	v_exp_f32_e32 v125, v125
	v_add_f32_e32 v122, v145, v122
	v_mfma_f32_16x16x32_bf16 v[94:97], v[94:97], v[66:69], v[110:113]
	v_sub_f32_e32 v118, v184, v213
	v_exp_f32_e32 v118, v118
	v_sub_f32_e32 v119, v185, v213
	v_mfma_f32_16x16x32_bf16 v[102:105], v[102:105], v[66:69], v[114:117]
	v_add_f32_e32 v122, v123, v122
	s_waitcnt vmcnt(15)
	ds_write_b128 v209, v[34:37]
	s_waitcnt vmcnt(14)
	ds_write_b128 v209, v[38:41] offset:1152
	s_waitcnt vmcnt(13)
	ds_write_b128 v209, v[42:45] offset:2304
	s_waitcnt vmcnt(12)
	ds_write_b128 v209, v[46:49] offset:3456
	s_waitcnt vmcnt(11)
	ds_write_b128 v209, v[50:53] offset:4608
	s_waitcnt vmcnt(10)
	ds_write_b128 v209, v[54:57] offset:5760
	s_waitcnt vmcnt(9)
	ds_write_b128 v209, v[58:61] offset:6912
	s_waitcnt vmcnt(8)
	ds_write_b128 v209, v[62:65] offset:8064
	v_exp_f32_e32 v114, v119
	v_mfma_f32_16x16x32_bf16 v[66:69], v[90:93], v[66:69], v[98:101]
	v_sub_f32_e32 v115, v182, v213
	v_cvt_pk_bf16_f32 v34, v198, v199
	v_cvt_pk_bf16_f32 v35, v196, v197
	v_mfma_f32_16x16x32_bf16 v[86:89], v[86:89], v[70:73], v[106:109]
	v_cvt_pk_bf16_f32 v36, v194, v195
	v_cvt_pk_bf16_f32 v37, v192, v193
	v_cvt_pk_bf16_f32 v38, v143, v144
	v_mfma_f32_16x16x32_bf16 v[78:81], v[78:81], v[70:73], v[94:97]
	v_cvt_pk_bf16_f32 v39, v145, v123
	v_cvt_pk_bf16_f32 v40, v124, v125
	v_cvt_pk_bf16_f32 v41, v118, v114
	v_mfma_f32_16x16x32_bf16 v[82:85], v[82:85], v[70:73], v[102:105]
	v_add_f32_e32 v122, v124, v122
	v_exp_f32_e32 v115, v115
	v_sub_f32_e32 v90, v183, v213
	v_mfma_f32_16x16x32_bf16 v[66:69], v[74:77], v[70:73], v[66:69]
	ds_read_b64_tr_b16 v[74:75], v208
	ds_read_b64_tr_b16 v[70:71], v208 offset:32
	ds_read_b64_tr_b16 v[62:63], v208 offset:64
	ds_read_b64_tr_b16 v[58:59], v208 offset:96
	ds_read_b64_tr_b16 v[76:77], v208 offset:2304
	ds_read_b64_tr_b16 v[72:73], v208 offset:2336
	ds_read_b64_tr_b16 v[64:65], v208 offset:2368
	ds_read_b64_tr_b16 v[60:61], v208 offset:2400
	ds_read_b64_tr_b16 v[54:55], v208 offset:4608
	ds_read_b64_tr_b16 v[50:51], v208 offset:4640
	ds_read_b64_tr_b16 v[46:47], v208 offset:4672
	ds_read_b64_tr_b16 v[42:43], v208 offset:4704
	ds_read_b64_tr_b16 v[56:57], v208 offset:6912
	ds_read_b64_tr_b16 v[52:53], v208 offset:6944
	ds_read_b64_tr_b16 v[48:49], v208 offset:6976
	ds_read_b64_tr_b16 v[44:45], v208 offset:7008
	s_waitcnt lgkmcnt(0)
; __device__ __forceinline__ void attn_phase(LAS unsigned char* lds, const bf16_t* QKV, const float* TBL  , bf16_t* O, int tid, int wave, int lane, int G) {
;     ...
;         for (int ip = 0; ip < 4; ++ip) {
; #pragma unroll
;             for (int rr = 0; rr < 2; ++rr) { LAS unsigned char* dst = vt + rr * 4608 + vkey * 144 + vch * 16;
; #pragma unroll
;                 for (int j = 0; j < 4; ++j) *(LAS u32x4*)(dst + j * 8 * 144) = vr[ip][rr][j]; }
;             union { u32x4 w; bf16x8 v; } pf0, pf1; pf0.w = pack8(s[2 * ip][0], s[2 * ip][1]); pf1.w = pack8(s[2 * ip + 1][0], s[2 * ip + 1][1]);
;             s16x4 ta0, ta1, ta2, ta3, tb0, tb1, tb2, tb3, ua0, ua1, ua2, ua3, ub0, ub1, ub2, ub3;
;             asm volatile("ds_read_b64_tr_b16 %0, %16\n\tds_read_b64_tr_b16 %1, %16 offset:32\n\tds_read_b64_tr_b16 %2, %16 offset:64\n\tds_read_b64_tr_b16 %3, %16 offset:96\n\t"
;                          "ds_read_b64_tr_b16 %4, %16 offset:2304\n\tds_read_b64_tr_b16 %5, %16 offset:2336\n\tds_read_b64_tr_b16 %6, %16 offset:2368\n\tds_read_b64_tr_b16 %7, %16 offset:2400\n\t"
;                          "ds_read_b64_tr_b16 %8, %16 offset:4608\n\tds_read_b64_tr_b16 %9, %16 offset:4640\n\tds_read_b64_tr_b16 %10, %16 offset:4672\n\tds_read_b64_tr_b16 %11, %16 offset:4704\n\t"
;                          "ds_read_b64_tr_b16 %12, %16 offset:6912\n\tds_read_b64_tr_b16 %13, %16 offset:6944\n\tds_read_b64_tr_b16 %14, %16 offset:6976\n\tds_read_b64_tr_b16 %15, %16 offset:7008\n\ts_waitcnt lgkmcnt(0)"
;                          : "=&v"(ta0), "=&v"(ta1), "=&v"(ta2), "=&v"(ta3), "=&v"(tb0), "=&v"(tb1), "=&v"(tb2), "=&v"(tb3), "=&v"(ua0), "=&v"(ua1), "=&v"(ua2), "=&v"(ua3), "=&v"(ub0), "=&v"(ub1), "=&v"(ub2), "=&v"(ub3) : "v"(ad) : "memory");
;             bf16x8 vf;
;             vf = (bf16x8){ta0[0], ta0[1], ta0[2], ta0[3], tb0[0], tb0[1], tb0[2], tb0[3]}; o[0] = __builtin_amdgcn_mfma_f32_16x16x32_bf16(vf, pf0.v, o[0], 0, 0, 0);
;             vf = (bf16x8){ta1[0], ta1[1], ta1[2], ta1[3], tb1[0], tb1[1], tb1[2], tb1[3]}; o[1] = __builtin_amdgcn_mfma_f32_16x16x32_bf16(vf, pf0.v, o[1], 0, 0, 0);
;             vf = (bf16x8){ta2[0], ta2[1], ta2[2], ta2[3], tb2[0], tb2[1], tb2[2], tb2[3]}; o[2] = __builtin_amdgcn_mfma_f32_16x16x32_bf16(vf, pf0.v, o[2], 0, 0, 0);
	v_add_f32_e32 v122, v125, v122
	v_exp_f32_e32 v90, v90
	v_mfma_f32_16x16x32_bf16 v[74:77], v[74:77], v[34:37], v[86:89]
	v_sub_f32_e32 v91, v180, v213
	v_add_f32_e32 v110, v118, v122
	v_exp_f32_e32 v91, v91
	v_sub_f32_e32 v92, v181, v213
	v_mfma_f32_16x16x32_bf16 v[62:65], v[62:65], v[34:37], v[78:81]
	v_add_f32_e32 v110, v114, v110
	v_exp_f32_e32 v92, v92
	v_sub_f32_e32 v94, v178, v213
	v_mfma_f32_16x16x32_bf16 v[70:73], v[70:73], v[34:37], v[82:85]
	v_add_f32_e32 v110, v115, v110
	v_exp_f32_e32 v94, v94
	v_sub_f32_e32 v95, v179, v213
	v_mfma_f32_16x16x32_bf16 v[34:37], v[58:61], v[34:37], v[66:69]
	v_add_f32_e32 v93, v90, v110
	v_exp_f32_e32 v86, v95
	v_sub_f32_e32 v87, v176, v213
	v_mfma_f32_16x16x32_bf16 v[54:57], v[54:57], v[38:41], v[74:77]
	v_add_f32_e32 v93, v91, v93
	v_exp_f32_e32 v87, v87
	v_sub_f32_e32 v82, v177, v213
	v_sub_f32_e32 v83, v174, v213
	v_sub_f32_e32 v79, v175, v213
	v_sub_f32_e32 v58, v172, v213
	v_sub_f32_e32 v59, v173, v213
	v_sub_f32_e32 v60, v170, v213
	v_sub_f32_e32 v61, v171, v213
	v_sub_f32_e32 v66, v168, v213
	v_mfma_f32_16x16x32_bf16 v[46:49], v[46:49], v[38:41], v[62:65]
	v_add_f32_e32 v93, v92, v93
	v_exp_f32_e32 v82, v82
	v_exp_f32_e32 v78, v83
	v_sub_f32_e32 v63, v169, v213
	v_exp_f32_e32 v79, v79
	v_exp_f32_e32 v58, v58
	v_exp_f32_e32 v59, v59
	v_exp_f32_e32 v60, v60
	v_mfma_f32_16x16x32_bf16 v[50:53], v[50:53], v[38:41], v[70:73]
	v_exp_f32_e32 v61, v61
	v_exp_f32_e32 v62, v66
	v_exp_f32_e32 v63, v63
	v_mfma_f32_16x16x32_bf16 v[34:37], v[42:45], v[38:41], v[34:37]
	s_waitcnt vmcnt(7)
	ds_write_b128 v209, v[2:5]
	s_waitcnt vmcnt(6)
	ds_write_b128 v209, v[6:9] offset:1152
	s_waitcnt vmcnt(5)
	ds_write_b128 v209, v[10:13] offset:2304
	s_waitcnt vmcnt(4)
	ds_write_b128 v209, v[14:17] offset:3456
	s_waitcnt vmcnt(3)
	ds_write_b128 v209, v[18:21] offset:4608
	s_waitcnt vmcnt(2)
	ds_write_b128 v209, v[22:25] offset:5760
	s_waitcnt vmcnt(1)
	ds_write_b128 v209, v[26:29] offset:6912
	s_waitcnt vmcnt(0)
	ds_write_b128 v209, v[30:33] offset:8064
	v_cvt_pk_bf16_f32 v2, v115, v90
	v_cvt_pk_bf16_f32 v3, v91, v92
	v_cvt_pk_bf16_f32 v4, v94, v86
	v_cvt_pk_bf16_f32 v5, v87, v82
	v_cvt_pk_bf16_f32 v6, v78, v79
	v_cvt_pk_bf16_f32 v7, v58, v59
	v_cvt_pk_bf16_f32 v8, v60, v61
	v_cvt_pk_bf16_f32 v9, v62, v63
	ds_read_b64_tr_b16 v[42:43], v208
	ds_read_b64_tr_b16 v[38:39], v208 offset:32
	ds_read_b64_tr_b16 v[30:31], v208 offset:64
	ds_read_b64_tr_b16 v[26:27], v208 offset:96
	ds_read_b64_tr_b16 v[44:45], v208 offset:2304
	ds_read_b64_tr_b16 v[40:41], v208 offset:2336
	ds_read_b64_tr_b16 v[32:33], v208 offset:2368
	ds_read_b64_tr_b16 v[28:29], v208 offset:2400
	ds_read_b64_tr_b16 v[22:23], v208 offset:4608
	ds_read_b64_tr_b16 v[18:19], v208 offset:4640
	ds_read_b64_tr_b16 v[14:15], v208 offset:4672
	ds_read_b64_tr_b16 v[10:11], v208 offset:4704
	ds_read_b64_tr_b16 v[24:25], v208 offset:6912
	ds_read_b64_tr_b16 v[20:21], v208 offset:6944
	ds_read_b64_tr_b16 v[16:17], v208 offset:6976
	ds_read_b64_tr_b16 v[12:13], v208 offset:7008
	s_waitcnt lgkmcnt(0)
	s_nop 0
	v_mfma_f32_16x16x32_bf16 v[42:45], v[42:45], v[2:5], v[54:57]
	s_nop 2
	v_add_f32_e32 v54, v94, v93
	v_add_f32_e32 v54, v86, v54
	v_add_f32_e32 v54, v87, v54
	v_mfma_f32_16x16x32_bf16 v[38:41], v[38:41], v[2:5], v[50:53]
	s_nop 2
	v_add_f32_e32 v50, v82, v54
	v_add_f32_e32 v50, v78, v50
	v_add_f32_e32 v50, v79, v50
	v_mfma_f32_16x16x32_bf16 v[30:33], v[30:33], v[2:5], v[46:49]
	s_nop 2
	v_add_f32_e32 v46, v58, v50
	v_add_f32_e32 v46, v59, v46
	v_add_f32_e32 v46, v60, v46
	v_mfma_f32_16x16x32_bf16 v[2:5], v[26:29], v[2:5], v[34:37]
	v_add_f32_e32 v26, v61, v46
	v_add_f32_e32 v26, v62, v26
	v_add_f32_e32 v26, v63, v26
	ds_bpermute_b32 v0, v0, v26
	v_mfma_f32_16x16x32_bf16 v[22:25], v[22:25], v[6:9], v[42:45]
	s_waitcnt lgkmcnt(0)
	v_add_f32_e32 v0, v26, v0
	ds_bpermute_b32 v26, v212, v0
	v_mfma_f32_16x16x32_bf16 v[18:21], v[18:21], v[6:9], v[38:41]
	s_waitcnt lgkmcnt(0)
	v_add_f32_e32 v0, v0, v26
	v_div_scale_f32 v26, s[10:11], v0, v0, 1.0
	v_rcp_f32_e32 v27, v26
	v_mfma_f32_16x16x32_bf16 v[14:17], v[14:17], v[6:9], v[30:33]
	v_mfma_f32_16x16x32_bf16 v[2:5], v[10:13], v[6:9], v[2:5]
	v_fma_f32 v6, -v26, v27, 1.0
	v_fmac_f32_e32 v27, v6, v27
	v_div_scale_f32 v6, vcc, 1.0, v0, 1.0
	v_mul_f32_e32 v7, v6, v27
	v_fma_f32 v8, -v26, v7, v6
	v_fmac_f32_e32 v7, v8, v27
	v_fma_f32 v6, -v26, v7, v6
	v_div_fmas_f32 v6, v6, v27, v7
	v_div_fixup_f32 v0, v6, v0, 1.0
	v_mul_f32_e32 v6, v0, v22
	v_mul_f32_e32 v7, v0, v23
	v_cvt_pk_bf16_f32 v6, v6, v7
	v_mul_f32_e32 v7, v0, v24
	v_mul_f32_e32 v8, v0, v25
	v_cvt_pk_bf16_f32 v7, v7, v8
	ds_write_b64 v211, v[6:7]
	v_mul_f32_e32 v6, v0, v18
	v_mul_f32_e32 v7, v0, v19
	v_cvt_pk_bf16_f32 v6, v6, v7
	v_mul_f32_e32 v7, v0, v20
	v_mul_f32_e32 v8, v0, v21
	v_cvt_pk_bf16_f32 v7, v7, v8
	ds_write_b64 v211, v[6:7] offset:32
	v_mul_f32_e32 v6, v0, v14
	v_mul_f32_e32 v7, v0, v15
	v_cvt_pk_bf16_f32 v6, v6, v7
	v_mul_f32_e32 v7, v0, v16
	v_mul_f32_e32 v2, v0, v2
	v_mul_f32_e32 v3, v0, v3
	v_mul_f32_e32 v8, v0, v17
	v_cvt_pk_bf16_f32 v7, v7, v8
	ds_write_b64 v211, v[6:7] offset:64
	v_cvt_pk_bf16_f32 v2, v2, v3
	v_mul_f32_e32 v3, v0, v4
	v_mul_f32_e32 v0, v0, v5
	v_cvt_pk_bf16_f32 v3, v3, v0
	ds_write_b64 v211, v[2:3] offset:96
	v_mov_b32_e32 v11, s9
	v_or_b32_e32 v10, s8, v164
	ds_read_b128 v[2:5], v209
	ds_read_b128 v[6:9], v209 offset:1152
	v_lshlrev_b64 v[10:11], 11, v[10:11]
	v_lshl_add_u64 v[10:11], s[44:45], 0, v[10:11]
	v_lshl_add_u64 v[10:11], v[10:11], 0, s[26:27]
	v_lshl_add_u64 v[10:11], v[10:11], 0, v[166:167]
	s_waitcnt lgkmcnt(1)
	global_store_dwordx4 v[10:11], v[2:5], off
	s_nop 1
	v_add_co_u32_e32 v2, vcc, 0x4000, v10
	s_nop 1
	v_addc_co_u32_e32 v3, vcc, 0, v11, vcc
	s_waitcnt lgkmcnt(0)
	global_store_dwordx4 v[2:3], v[6:9], off
	s_waitcnt lgkmcnt(0)
	s_cbranch_scc0 .LBB0_372
